# stack5 + late weight conversions of CUs>=128 moved behind their GEMM unit in P4/P5/P7
# baseline (speedup 1.0000x reference)
; #define LAS __attribute__((address_space(3)))
; #define GAS __attribute__((address_space(1)))
; __device__ __forceinline__ unsigned pk2(float lo, float hi) { const f32x2pk v = {lo, hi}; return __builtin_bit_cast(unsigned, __builtin_convertvector(v, bf16x2pk)); }
; #define LDS_WAIT() asm volatile("s_waitcnt lgkmcnt(0)" ::: "memory")
; __device__ __forceinline__ int colpos(int n0) { const int a = n0 & 255; return (n0 & ~255) + 128 * ((a >> 5) & 1) + 32 * (a >> 6); }
; #define LATE_TRANSPOSE(NIT, CALL) do { if (G == 256 && bid >= 128) { LAS float* scr = (LAS float*)(lds + wave * 16384); \
;         for (int r = (bid - 128) * 8 + wave; r < (NIT); r += 1024) { CALL; } } } while (0)
;     const int nblk = N / 32, kb = item / nblk, nb = item % nblk, k0 = 64 * kb, n0 = 32 * nb;
;     float wv[32];
; #pragma unroll
;     for (int i = 0; i < 32; ++i) wv[i] = W[(size_t)(k0 + 2 * i + (lane >> 5)) * N + n0 + (lane & 31)];
;     if (kgain) {
; #pragma unroll
;         for (int i = 0; i < 32; ++i) wv[i] *= kgain[k0 + 2 * i + (lane >> 5)]; }
; #pragma unroll
;     for (int i = 0; i < 32; ++i) scr[(2 * i + (lane >> 5)) * 33 + (lane & 31)] = wv[i];
;     LDS_WAIT(); asm volatile("" ::: "memory");
;     const int c = lane & 7; const int prow = row_off + (posmode == 0 ? colpos(n0) : 256 * (n0 >> 7) + 32 * ((n0 >> 5) & 3) + (posmode == 2 ? 128 : 0));
; #pragma unroll
;     for (int j = 0; j < 4; ++j) { const int n = (lane >> 3) + 8 * j; const LAS float* s = scr + (8 * c) * 33 + n;
;         u32x4 o; o.x = pk2(s[0 * 33], s[1 * 33]); o.y = pk2(s[2 * 33], s[3 * 33]); o.z = pk2(s[4 * 33], s[5 * 33]); o.w = pk2(s[6 * 33], s[7 * 33]);
;         *(GAS u32x4*)(WT + (size_t)(prow + n) * K + k0 + 8 * c) = o; }
;     LDS_WAIT(); asm volatile("" ::: "memory");
; }
; __global__ void __launch_bounds__(512, 2) mk_fwd(Args a) {
;     ...
;     if (IN(4)) {
;         __syncthreads();
;         LATE_TRANSPOSE((FF / 64) * (1024 / 32), transpose_item(INF(I_WD), FF, 1024, (bf16*)(ws + WS_WD), 0, scr, r, lane));
.LBB0_664:
	s_mov_b32 s0, 0
	v_writelane_b32 v255, s0, 53
	s_cmp_lt_i32 s84, 5
	s_cselect_b64 s[0:1], -1, 0
	s_cmp_gt_i32 s85, 4
	s_cselect_b64 s[2:3], -1, 0
	s_and_b64 s[0:1], s[0:1], s[2:3]
	s_andn2_b64 vcc, exec, s[0:1]
	s_cbranch_vccnz .LBB0_773
	s_cmpk_lg_i32 s75, 0x100
	s_cselect_b64 s[0:1], -1, 0
	s_cmpk_lt_i32 s96, 0x80
	s_cselect_b64 s[2:3], -1, 0
	s_or_b64 s[0:1], s[2:3], s[0:1]
	s_and_b64 vcc, exec, s[0:1]
	s_waitcnt lgkmcnt(0)
	s_barrier
	s_branch .LBB0_669
.Lp4_late:
	v_readlane_b32 s0, v255, 1
	s_add_i32 s4, s0, 0xfffffc00
	s_cmpk_gt_i32 s4, 0x57f
	v_readlane_b32 s1, v255, 2
	s_cbranch_scc1 .LBB0_669
	v_readlane_b32 s0, v254, 63
	s_lshl_b32 s0, s0, 14
	v_and_b32_e32 v2, 31, v0
	v_readlane_b32 s8, v254, 0
	s_add_i32 s2, s0, 0
	v_lshlrev_b32_e32 v4, 2, v2
	v_mov_b32_e32 v5, 0
	v_readlane_b32 s14, v254, 6
	v_readlane_b32 s15, v254, 7
	v_add_u32_e32 v11, s2, v4
	v_lshrrev_b32_e32 v1, 5, v252
	v_lshl_add_u64 v[2:3], s[14:15], 0, v[4:5]
	v_lshlrev_b32_e32 v4, 3, v0
	v_and_b32_e32 v4, 56, v4
	v_mul_u32_u24_e32 v12, 0x84, v1
	v_lshrrev_b32_e32 v6, 3, v252
	v_mul_u32_u24_e32 v7, 0x84, v4
	v_lshlrev_b32_e32 v4, 1, v4
	v_lshl_add_u64 v[4:5], s[94:95], 0, v[4:5]
	s_mov_b64 s[0:1], 0x1d00000
	v_lshlrev_b32_e32 v8, 2, v6
	v_add_u32_e32 v11, v11, v12
	v_lshl_add_u64 v[4:5], v[4:5], 0, s[0:1]
	v_add3_u32 v7, s2, v7, v8
	v_or_b32_e32 v8, 8, v6
	v_or_b32_e32 v9, 16, v6
	v_or_b32_e32 v10, 24, v6
	s_lshl_b32 s5, s4, 5
	s_lshl_b32 s6, s4, 7
	s_movk_i32 s7, 0xb00
	v_add_u32_e32 v12, 0x400, v11
	v_add_u32_e32 v13, 0x800, v11
	v_add_u32_e32 v14, 0xc00, v11
	v_add_u32_e32 v15, 0x1000, v11
	v_add_u32_e32 v16, 0x1400, v11
	v_add_u32_e32 v17, 0x1800, v11
	v_add_u32_e32 v18, 0x1c00, v11
	v_readlane_b32 s9, v254, 1
	v_readlane_b32 s10, v254, 2
	v_readlane_b32 s11, v254, 3
	v_readlane_b32 s12, v254, 4
	v_readlane_b32 s13, v254, 5

; #define LAS __attribute__((address_space(3)))
; template <int NKS, bool ATILED = false, bool FFN = false, bool HALF = false, class EF> ...
;     const int lane = tid & 63, w = __builtin_amdgcn_readfirstlane(tid >> 6), c16 = lane & 15, kq = lane >> 4;
;     static_assert(NKS % 2 == 0, "the waves' K slices are whole 32-wide k-steps");
;     constexpr int kw = NKS * 16, K = kw * 8, NS = NKS / 2;
;     constexpr int RB = HALF ? 32 : 64, MI = RB / 16; const int ncb = N >> 6, npieces = (512 / RB) * ncb;
;     if (bid < first || bid >= first + ncu) return;
;     LAS float* lf = (LAS float*)lds;
; #pragma unroll 1
;     for (int pc = bid - first;; pc += ncu) {
;         if (qctr) { __syncthreads(); if (tid == 0) qslot[0] = (int)atomicAdd(qctr, 1u); __syncthreads(); pc = __builtin_amdgcn_readfirstlane(qslot[0]); }
;         if (pc >= npieces) break;
;         const int rb = pc / ncb, cb = pc - rb * ncb;
;         const bf16* a0 = ATILED ? A + (size_t)(MP + RB * rb + c16) * 64 : A + (size_t)(RB * rb + c16) * K + w * kw + 8 * kq;
;         const bf16* b0 = Wt + (size_t)((cb >> 2) * 256 + 32 * (cb & 3) + c16) * K + w * kw + 8 * kq;
; __global__ void __launch_bounds__(512, 2) mk_fwd(Args a) {
;     ...
;         mini_gemm<8>((const bf16*)(ws + WS_MIX) + (size_t)MP * DMODEL, (const bf16*)(ws + WS_WOUT), DMODEL, 0, G, bid, lds, tid,
;                   mef::Res<false>{INF(I_XS), (bf16*)(ws + WS_XB1), (float*)(ws + WS_SS1)});
.LBB0_669:
	v_readlane_b32 s0, v255, 53
	s_cmp_lg_u32 s0, 0
	s_cbranch_scc1 .Lp4_after
	s_add_u32 s33, s94, 0xb00000
	s_addc_u32 s34, s95, 0
	s_add_u32 s6, s94, 0x13200000
	s_addc_u32 s7, s95, 0
	s_add_u32 s8, s94, 0x3200000
	s_addc_u32 s9, s95, 0
	s_cmp_lt_i32 s96, 0
	s_cselect_b64 s[2:3], -1, 0
	s_cmp_ge_i32 s96, s75
	s_cselect_b64 s[4:5], -1, 0
	s_or_b64 s[2:3], s[2:3], s[4:5]
	s_cmpk_gt_u32 s96, 0x7f
	s_cselect_b64 s[4:5], -1, 0
	v_and_b32_e32 v18, 15, v0
	s_or_b64 s[2:3], s[2:3], s[4:5]
	v_readfirstlane_b32 s0, v0
	s_andn2_b64 vcc, exec, s[2:3]
	v_lshlrev_b32_e32 v20, 2, v18
	s_cbranch_vccz .LBB0_674
	s_lshr_b32 s2, s0, 6
	s_lshl_b32 s3, s2, 8
	v_bfe_u32 v19, v0, 4, 2
	s_add_u32 s0, s94, s3
	s_addc_u32 s1, s95, 0
	v_lshlrev_b32_e32 v4, 4, v19
	v_mov_b32_e32 v5, 0
	v_lshl_add_u64 v[2:3], s[0:1], 0, v[4:5]
	s_mov_b64 s[0:1], 0xef00000
	v_lshl_add_u64 v[2:3], v[2:3], 0, s[0:1]
	s_add_u32 s0, s33, s3
	s_addc_u32 s1, s34, 0
	v_lshlrev_b32_e32 v7, 3, v0
	v_lshl_add_u64 v[4:5], s[0:1], 0, v[4:5]
	s_lshl_b32 s0, s2, 14
	v_lshrrev_b32_e32 v1, 3, v0
	v_and_b32_e32 v22, 56, v7
	v_lshlrev_b32_e32 v6, 10, v19
	s_add_i32 s0, s0, 0
	v_lshlrev_b32_e32 v7, 8, v1
	v_lshlrev_b32_e32 v8, 2, v22
	v_add3_u32 v23, 0, v7, v8
	v_and_b32_e32 v7, 7, v0
	v_add3_u32 v24, s0, v20, v6
	v_lshlrev_b32_e32 v21, 3, v19
	v_cmp_eq_u32_e32 vcc, 0, v7
	s_mov_b32 s4, 0x10000
	v_add_u32_e32 v25, 0x10000, v23
	v_add_u32_e32 v26, 0x10010, v23
	v_add_u32_e32 v27, 0x14000, v23
	v_add_u32_e32 v28, 0x14010, v23
	s_mov_b32 s5, 0x18000
	v_add_u32_e32 v29, 0x18000, v23
	v_add_u32_e32 v30, 0x18010, v23
	v_add_u32_e32 v31, 0x1c000, v23
	v_add_u32_e32 v32, 0x1c010, v23
	s_lshl_b32 s10, s96, 5
	s_lshl_b32 s11, s75, 5
	s_lshl_b32 s12, s96, 6
	s_lshl_b32 s13, s75, 6
	s_mov_b32 s14, 0x8000
	s_mov_b32 s15, 0x40000
	s_mov_b32 s16, 0x48000
	s_mov_b64 s[2:3], 0x4000
	v_add_u32_e32 v33, 0x1000, v24
	v_add_u32_e32 v34, 0x2000, v24
	v_add_u32_e32 v35, 0x3000, v24
	s_mov_b32 s17, s96
	s_branch .LBB0_672

; #define PG8_WAIT_V(n) asm volatile("s_waitcnt vmcnt(" #n ")" ::: "memory")
; #define PG8_BAR __builtin_amdgcn_s_barrier()
; #define GRID_BAR() do { if (MK_ONE_LAUNCH) { xcd_barrier(bar); if (MK_DBL == 99) xcd_barrier(bar); } } while (0)
; #define BOTH(k) (IN(k) && IN((k) + 1))
; template <class Epi, class Sched, bool ALIGN_EPI = false, bool SP2 = false>
; __device__ __forceinline__ void gemm_phase(PG8_LAS unsigned char* lds, const Gemm g, const Sched& S, const Epi& E) {
;     ...
;     PG8_WAIT_V(0);
;     if constexpr (!ALIGN_EPI) { if (wr == 0) PG8_BAR; }
;     PG8_BAR;
; __global__ void __launch_bounds__(512, 2) mk_fwd(Args a) {
;     ...
;         if (BOTH(4)) GRID_BAR();
.LBB0_715:
	s_waitcnt vmcnt(0)
	s_barrier
	s_cmpk_lg_i32 s75, 0x100
	s_cbranch_scc1 .Lp4_after
	s_cmpk_lt_i32 s96, 0x80
	s_cbranch_scc1 .Lp4_after
	s_mov_b32 s0, 1
	v_writelane_b32 v255, s0, 53
	s_branch .Lp4_late
.Lp4_after:
	s_cmp_lt_i32 s85, 6
	s_cbranch_scc1 .LBB0_773
	s_branch .LBB0_720

; #define LATE_TRANSPOSE(NIT, CALL) do { if (G == 256 && bid >= 128) { LAS float* scr = (LAS float*)(lds + wave * 16384); \
;         for (int r = (bid - 128) * 8 + wave; r < (NIT); r += 1024) { CALL; } } } while (0)
; __global__ void __launch_bounds__(512, 2) mk_fwd(Args a) {
;     ...
;     if (IN(5)) {
;         __syncthreads();
;         LATE_TRANSPOSE((1024 / 64) * (1024 / 32), transpose_item(INF(I_WO), 1024, 1024, (bf16*)(ws + WS_WO), 0, scr, r, lane));
;         LATE_TRANSPOSE((1024 / 64) * (FF / 32), transpose_item(INF(I_WG), 1024, FF, (bf16*)(ws + WS_WG), 0, scr, r, lane, INF(I_LN3), 1));
;         mini_gemm<8>((const bf16*)(ws + WS_XB1) + (size_t)MP * DMODEL, (const bf16*)(ws + WS_WQ), DMODEL, 0, G, bid, lds, tid,
;                   mef::Cq{(const float*)(ws + WS_SS1), (bf16*)(ws + WS_CQ), (float*)(ws + WS_SSQ), INF(I_CAQG)});
.LBB0_773:
	s_mov_b32 s0, 0
	v_writelane_b32 v255, s0, 53
	s_cmp_lt_i32 s84, 6
	s_cselect_b64 s[0:1], -1, 0
	s_cmp_gt_i32 s85, 5
	s_cselect_b64 s[2:3], -1, 0
	s_and_b64 s[0:1], s[0:1], s[2:3]
	s_andn2_b64 vcc, exec, s[0:1]
	s_cbranch_vccnz .LBB0_873
	s_cmpk_lg_i32 s75, 0x100
	s_cselect_b64 s[0:1], -1, 0
	s_cmpk_lt_i32 s96, 0x80
	s_cselect_b64 s[2:3], -1, 0
	s_or_b64 s[0:1], s[2:3], s[0:1]
	s_and_b64 vcc, exec, s[0:1]
	s_waitcnt lgkmcnt(0)
	s_barrier
	s_branch .LBB0_783
.Lp5_late:
	v_readlane_b32 s0, v254, 63
	s_lshl_b32 s0, s0, 14
	s_add_i32 s4, s0, 0
	v_readlane_b32 s0, v255, 1
	s_add_i32 s6, s0, 0xfffffc00
	s_cmpk_gt_i32 s6, 0x1ff
	v_readlane_b32 s1, v255, 2
	s_cbranch_scc1 .LBB0_778
	v_and_b32_e32 v2, 31, v0
	v_readlane_b32 s8, v254, 42
	v_lshlrev_b32_e32 v4, 2, v2
	v_mov_b32_e32 v5, 0
	v_readlane_b32 s18, v254, 52
	v_readlane_b32 s19, v254, 53
	v_add_u32_e32 v11, s4, v4
	v_lshrrev_b32_e32 v1, 5, v252
	v_lshl_add_u64 v[2:3], s[18:19], 0, v[4:5]
	v_lshlrev_b32_e32 v4, 3, v0
	v_and_b32_e32 v4, 56, v4
	v_mul_u32_u24_e32 v12, 0x84, v1
	v_lshrrev_b32_e32 v6, 3, v252
	v_mul_u32_u24_e32 v7, 0x84, v4
	v_lshlrev_b32_e32 v4, 1, v4
	v_lshl_add_u64 v[4:5], s[94:95], 0, v[4:5]
	s_mov_b64 s[0:1], 0xf00000
	v_lshlrev_b32_e32 v8, 2, v6
	v_add_u32_e32 v11, v11, v12
	v_lshl_add_u64 v[4:5], v[4:5], 0, s[0:1]
	v_add3_u32 v7, s4, v7, v8
	v_or_b32_e32 v8, 8, v6
	v_or_b32_e32 v9, 16, v6
	v_or_b32_e32 v10, 24, v6
	s_lshl_b32 s5, s6, 5
	s_lshl_b32 s7, s6, 7
	v_add_u32_e32 v12, 0x400, v11
	v_add_u32_e32 v13, 0x800, v11
	v_add_u32_e32 v14, 0xc00, v11
	v_add_u32_e32 v15, 0x1000, v11
	v_add_u32_e32 v16, 0x1400, v11
	v_add_u32_e32 v17, 0x1800, v11
	v_add_u32_e32 v18, 0x1c00, v11
	s_mov_b32 s8, s6
	v_readlane_b32 s9, v254, 43
	v_readlane_b32 s10, v254, 44
	v_readlane_b32 s11, v254, 45
	v_readlane_b32 s12, v254, 46
	v_readlane_b32 s13, v254, 47
	v_readlane_b32 s14, v254, 48
	v_readlane_b32 s15, v254, 49
	v_readlane_b32 s16, v254, 50
	v_readlane_b32 s17, v254, 51
	v_readlane_b32 s20, v254, 54
	v_readlane_b32 s21, v254, 55
	v_readlane_b32 s22, v254, 56
	v_readlane_b32 s23, v254, 57

; #define LAS __attribute__((address_space(3)))
; template <int NKS, bool ATILED = false, bool FFN = false, bool HALF = false, class EF> ...
;     const int lane = tid & 63, w = __builtin_amdgcn_readfirstlane(tid >> 6), c16 = lane & 15, kq = lane >> 4;
;     static_assert(NKS % 2 == 0, "the waves' K slices are whole 32-wide k-steps");
;     constexpr int kw = NKS * 16, K = kw * 8, NS = NKS / 2;
;     constexpr int RB = HALF ? 32 : 64, MI = RB / 16; const int ncb = N >> 6, npieces = (512 / RB) * ncb;
;     if (bid < first || bid >= first + ncu) return;
;     LAS float* lf = (LAS float*)lds;
; #pragma unroll 1
;     for (int pc = bid - first;; pc += ncu) {
;         if (qctr) { __syncthreads(); if (tid == 0) qslot[0] = (int)atomicAdd(qctr, 1u); __syncthreads(); pc = __builtin_amdgcn_readfirstlane(qslot[0]); }
;         if (pc >= npieces) break;
;         const int rb = pc / ncb, cb = pc - rb * ncb;
;         const bf16* a0 = ATILED ? A + (size_t)(MP + RB * rb + c16) * 64 : A + (size_t)(RB * rb + c16) * K + w * kw + 8 * kq;
;         const bf16* b0 = Wt + (size_t)((cb >> 2) * 256 + 32 * (cb & 3) + c16) * K + w * kw + 8 * kq;
; __global__ void __launch_bounds__(512, 2) mk_fwd(Args a) {
;     ...
;         mini_gemm<8>((const bf16*)(ws + WS_XB1) + (size_t)MP * DMODEL, (const bf16*)(ws + WS_WQ), DMODEL, 0, G, bid, lds, tid,
;                   mef::Cq{(const float*)(ws + WS_SS1), (bf16*)(ws + WS_CQ), (float*)(ws + WS_SSQ), INF(I_CAQG)});
.LBB0_783:
	v_readlane_b32 s0, v255, 53
	s_cmp_lg_u32 s0, 0
	s_cbranch_scc1 .Lp5_after
	s_add_u32 s19, s94, 0xd00000
	s_addc_u32 s33, s95, 0
	s_add_u32 s8, s94, 0x3200000
	s_addc_u32 s9, s95, 0
	s_add_u32 s10, s94, 0x15300000
	s_addc_u32 s11, s95, 0
	s_cmp_lt_i32 s96, 0
	s_cselect_b64 s[2:3], -1, 0
	s_cmp_ge_i32 s96, s75
	s_cselect_b64 s[4:5], -1, 0
	s_or_b64 s[2:3], s[2:3], s[4:5]
	s_cmpk_gt_u32 s96, 0x7f
	s_cselect_b64 s[4:5], -1, 0
	v_and_b32_e32 v28, 15, v0
	s_or_b64 s[2:3], s[2:3], s[4:5]
	v_readfirstlane_b32 s0, v0
	s_andn2_b64 vcc, exec, s[2:3]
	v_lshlrev_b32_e32 v30, 2, v28
	s_cbranch_vccz .LBB0_788
	s_add_u32 s4, s94, 0x3600000
	s_addc_u32 s5, s95, 0
	s_lshr_b32 s2, s0, 6
	s_lshl_b32 s3, s2, 8
	v_bfe_u32 v29, v0, 4, 2
	s_add_u32 s0, s94, s3
	s_addc_u32 s1, s95, 0
	v_lshlrev_b32_e32 v2, 4, v29
	v_mov_b32_e32 v3, 0
	v_lshl_add_u64 v[4:5], s[0:1], 0, v[2:3]
	s_mov_b64 s[0:1], 0x15200000
	v_lshl_add_u64 v[10:11], v[4:5], 0, s[0:1]
	s_add_u32 s0, s19, s3
	s_addc_u32 s1, s33, 0
	v_lshl_add_u64 v[12:13], s[0:1], 0, v[2:3]
	v_lshlrev_b32_e32 v3, 3, v0
	s_lshl_b32 s0, s2, 14
	v_lshrrev_b32_e32 v1, 3, v0
	v_and_b32_e32 v32, 56, v3
	v_lshlrev_b32_e32 v2, 10, v29
	s_add_i32 s0, s0, 0
	v_lshlrev_b32_e32 v3, 8, v1
	v_lshlrev_b32_e32 v4, 2, v32
	v_add3_u32 v33, 0, v3, v4
	v_and_b32_e32 v3, 7, v0
	v_add3_u32 v34, s0, v30, v2
	v_lshlrev_b32_e32 v31, 3, v29
	v_cmp_eq_u32_e64 s[2:3], 0, v3
	s_mov_b32 s13, 0x10000
	v_add_u32_e32 v35, 0x10000, v33
	v_add_u32_e32 v36, 0x10010, v33
	v_add_u32_e32 v37, 0x14000, v33
	v_add_u32_e32 v38, 0x14010, v33
	s_mov_b32 s14, 0x18000
	v_add_u32_e32 v39, 0x18000, v33
	v_add_u32_e32 v40, 0x18010, v33
	v_add_u32_e32 v41, 0x1c000, v33
	v_add_u32_e32 v42, 0x1c010, v33
	s_lshl_b32 s15, s96, 5
	s_lshl_b32 s16, s75, 5
	s_lshl_b32 s17, s96, 6
	s_lshl_b32 s18, s75, 6
	s_mov_b32 s20, 0x8000
	s_mov_b32 s21, 0x40000
	s_mov_b32 s22, 0x48000
	s_mov_b64 s[6:7], 0x4000
	v_mov_b32_e32 v43, 0x358637bd
	s_mov_b32 s23, 0xf800000
	v_mov_b32_e32 v44, 0x260
	s_mov_b32 s12, 0x3db8aa3b
	v_add_u32_e32 v45, 0x1000, v34
	v_add_u32_e32 v46, 0x2000, v34
	v_add_u32_e32 v47, 0x3000, v34
	s_mov_b32 s24, s96
	s_branch .LBB0_786

; __device__ __forceinline__ unsigned xb_ld(unsigned* p)              { return __hip_atomic_load(p, __ATOMIC_RELAXED, __HIP_MEMORY_SCOPE_AGENT); }
; #define GRID_BAR() do { if (MK_ONE_LAUNCH) { xcd_barrier(bar); if (MK_DBL == 99) xcd_barrier(bar); } } while (0)
; #define BOTH(k) (IN(k) && IN((k) + 1))
; __device__ __forceinline__ void xcd_barrier_complete(unsigned* bar, unsigned x, unsigned& nloc, unsigned& nx) {
;     const unsigned G = gridDim.x * gridDim.y * gridDim.z;
;     unsigned sum, cnt, mine, sp = 0u;
;     for (;;) {
;         sum = 0u; cnt = 0u; mine = 0u;
; #pragma unroll
;         for (unsigned j = 0; j < 16; ++j) { const unsigned c = xb_ld(&bar[XB_XCNT(j)]); sum += c; cnt += (c > 0u) ? 1u : 0u; mine = (j == x) ? c : mine; }
; __device__ __forceinline__ void xcd_barrier(const XcdBarrier& b) {
;     asm volatile("s_waitcnt vmcnt(0)" ::: "memory");
;     __syncthreads();
;     if (threadIdx.x == 0) {
;         unsigned* bar = b.bar;
;         __builtin_amdgcn_s_waitcnt(0);
;         unsigned nloc = b.st[0], nx = b.st[1];
;         if (nloc == 0u) { xcd_barrier_complete(bar, b.x, nloc, nx); b.st[0] = nloc; b.st[1] = nx; }
; __global__ void __launch_bounds__(512, 2) mk_fwd(Args a) {
;     ...
;         if (BOTH(5)) GRID_BAR();
.Lp5_after:
.LBB0_819:
	s_cmp_lt_i32 s85, 7
	s_cbranch_scc1 .LBB0_873
	s_waitcnt vmcnt(0)
	s_barrier
	s_mov_b64 s[0:1], exec
	v_readlane_b32 s2, v254, 61
	v_readlane_b32 s3, v254, 62
	s_and_b64 s[2:3], s[0:1], s[2:3]
	s_mov_b64 exec, s[2:3]
	s_cbranch_execz .LBB0_872
	s_add_i32 s2, 0, 0x20060
	v_mov_b32_e32 v1, s2
	s_waitcnt vmcnt(0) expcnt(0) lgkmcnt(0)
	ds_read_b32 v3, v1
	s_add_i32 s2, 0, 0x20064
	v_mov_b32_e32 v1, s2
	ds_read_b32 v1, v1
	s_waitcnt lgkmcnt(1)
	v_cmp_ne_u32_e32 vcc, 0, v3
	s_cbranch_vccnz .LBB0_836
	v_readlane_b32 s2, v254, 8
	v_readlane_b32 s3, v254, 9
	s_load_dwordx2 s[6:7], s[2:3], 0x4
	s_add_u32 s2, s94, 0x4200
	s_addc_u32 s3, s95, 0
	s_add_u32 s4, s94, 0x4400
	s_addc_u32 s5, s95, 0
	s_waitcnt lgkmcnt(0)
	s_mul_i32 s33, s6, s75
	s_add_u32 s6, s94, 0x4500
	s_mul_i32 s33, s33, s7
	s_addc_u32 s7, s95, 0
	s_add_u32 s8, s94, 0x4600
	s_addc_u32 s9, s95, 0
	s_add_u32 s10, s94, 0x4700
	s_addc_u32 s11, s95, 0
	s_add_u32 s12, s94, 0x4800
	s_addc_u32 s13, s95, 0
	s_add_u32 s14, s94, 0x4900
	s_addc_u32 s15, s95, 0
	s_add_u32 s16, s94, 0x4a00
	s_addc_u32 s17, s95, 0
	s_add_u32 s18, s94, 0x4b00
	s_addc_u32 s19, s95, 0
	s_add_u32 s20, s94, 0x4c00
	s_addc_u32 s21, s95, 0
	s_add_u32 s22, s94, 0x4d00
	s_addc_u32 s23, s95, 0
	s_add_u32 s24, s94, 0x4e00
	s_addc_u32 s25, s95, 0
	s_add_u32 s26, s94, 0x4f00
	s_addc_u32 s27, s95, 0
	s_add_u32 s28, s94, 0x5000
	s_addc_u32 s29, s95, 0
	s_add_u32 s30, s94, 0x5100
	s_addc_u32 s31, s95, 0
	s_add_u32 s34, s94, 0x5200
	s_addc_u32 s35, s95, 0
	s_add_u32 s42, s94, 0x5300
	s_addc_u32 s43, s95, 0
	s_mov_b32 s50, 1
	v_mov_b32_e32 v17, 0
	s_branch .LBB0_824

; #define LAS __attribute__((address_space(3)))
; #define GAS __attribute__((address_space(1)))
; __device__ __forceinline__ unsigned pk2(float lo, float hi) { const f32x2pk v = {lo, hi}; return __builtin_bit_cast(unsigned, __builtin_convertvector(v, bf16x2pk)); }
; #define LDS_WAIT() asm volatile("s_waitcnt lgkmcnt(0)" ::: "memory")
; __device__ __forceinline__ int colpos(int n0) { const int a = n0 & 255; return (n0 & ~255) + 128 * ((a >> 5) & 1) + 32 * (a >> 6); }
; #define LATE_TRANSPOSE(NIT, CALL) do { if (G == 256 && bid >= 128) { LAS float* scr = (LAS float*)(lds + wave * 16384); \
;         for (int r = (bid - 128) * 8 + wave; r < (NIT); r += 1024) { CALL; } } } while (0)
;     const int nblk = N / 32, kb = item / nblk, nb = item % nblk, k0 = 64 * kb, n0 = 32 * nb;
;     float wv[32];
; #pragma unroll
;     for (int i = 0; i < 32; ++i) wv[i] = W[(size_t)(k0 + 2 * i + (lane >> 5)) * N + n0 + (lane & 31)];
;     if (kgain) {
; #pragma unroll
;         for (int i = 0; i < 32; ++i) wv[i] *= kgain[k0 + 2 * i + (lane >> 5)]; }
; #pragma unroll
;     for (int i = 0; i < 32; ++i) scr[(2 * i + (lane >> 5)) * 33 + (lane & 31)] = wv[i];
;     LDS_WAIT(); asm volatile("" ::: "memory");
;     const int c = lane & 7; const int prow = row_off + (posmode == 0 ? colpos(n0) : 256 * (n0 >> 7) + 32 * ((n0 >> 5) & 3) + (posmode == 2 ? 128 : 0));
; #pragma unroll
;     for (int j = 0; j < 4; ++j) { const int n = (lane >> 3) + 8 * j; const LAS float* s = scr + (8 * c) * 33 + n;
;         u32x4 o; o.x = pk2(s[0 * 33], s[1 * 33]); o.y = pk2(s[2 * 33], s[3 * 33]); o.z = pk2(s[4 * 33], s[5 * 33]); o.w = pk2(s[6 * 33], s[7 * 33]);
;         *(GAS u32x4*)(WT + (size_t)(prow + n) * K + k0 + 8 * c) = o; }
;     LDS_WAIT(); asm volatile("" ::: "memory");
; }
; __global__ void __launch_bounds__(512, 2) mk_fwd(Args a) {
;     ...
;     if (IN(7)) {
;         __syncthreads();
;         LATE_TRANSPOSE((1024 / 64) * (FF / 32), transpose_item(INF(I_WVV), 1024, FF, (bf16*)(ws + WS_WG), 0, scr, r, lane, INF(I_LN3), 2));
.LBB0_945:
	s_mov_b32 s0, 0
	v_writelane_b32 v255, s0, 53
	s_cmp_lt_i32 s84, 8
	s_cselect_b64 s[0:1], -1, 0
	s_cmp_gt_i32 s85, 7
	s_cselect_b64 s[2:3], -1, 0
	s_and_b64 s[0:1], s[0:1], s[2:3]
	s_andn2_b64 vcc, exec, s[0:1]
	s_cbranch_vccnz .LBB0_1056
	s_cmpk_lg_i32 s75, 0x100
	s_cselect_b64 s[0:1], -1, 0
	s_cmpk_lt_i32 s96, 0x80
	s_cselect_b64 s[2:3], -1, 0
	s_or_b64 s[0:1], s[2:3], s[0:1]
	s_and_b64 vcc, exec, s[0:1]
	s_waitcnt lgkmcnt(0)
	s_barrier
	s_branch .LBB0_952
.Lp7_late:
	v_and_b32_e32 v252, 63, v0
	v_readlane_b32 s0, v255, 1
	s_add_i32 s6, s0, 0xfffffc00
	s_cmpk_gt_i32 s6, 0x57f
	v_readlane_b32 s1, v255, 2
	s_cbranch_scc1 .LBB0_952
	v_readlane_b32 s0, v254, 63
	v_and_b32_e32 v2, 31, v0
	v_readlane_b32 s8, v254, 0
	s_lshl_b32 s0, s0, 14
	v_lshlrev_b32_e32 v4, 2, v2
	v_mov_b32_e32 v5, 0
	v_readlane_b32 s9, v254, 1
	v_readlane_b32 s10, v254, 2
	v_readlane_b32 s11, v254, 3
	v_readlane_b32 s12, v254, 4
	v_readlane_b32 s13, v254, 5
	v_readlane_b32 s14, v254, 6
	v_readlane_b32 s15, v254, 7
	s_add_i32 s4, s0, 0
	v_lshl_add_u64 v[2:3], s[8:9], 0, v[4:5]
	v_readlane_b32 s8, v254, 42
	v_readlane_b32 s20, v254, 54
	v_readlane_b32 s21, v254, 55
	v_add_u32_e32 v6, s4, v4
	v_lshlrev_b32_e32 v4, 3, v0
	s_cmp_lg_u64 s[20:21], 0
	v_lshrrev_b32_e32 v40, 3, v252
	v_and_b32_e32 v4, 56, v4
	v_lshrrev_b32_e32 v1, 5, v252
	s_cselect_b64 s[0:1], -1, 0
	v_mul_u32_u24_e32 v8, 0x84, v4
	v_lshlrev_b32_e32 v4, 1, v4
	v_lshlrev_b32_e32 v9, 2, v40
	v_readlane_b32 s9, v254, 43
	v_mul_u32_u24_e32 v7, 0x84, v1
	v_lshl_add_u64 v[4:5], s[94:95], 0, v[4:5]
	s_mov_b64 s[2:3], 0x1100000
	v_add3_u32 v41, s4, v8, v9
	v_cndmask_b32_e64 v8, 0, 1, s[0:1]
	v_lshl_add_u64 v[4:5], v[4:5], 0, s[2:3]
	v_or_b32_e32 v42, 8, v40
	v_or_b32_e32 v43, 16, v40
	v_or_b32_e32 v44, 24, v40
	s_lshl_b32 s7, s6, 5
	s_lshl_b32 s8, s6, 6
	s_movk_i32 s9, 0x2c00
	v_cmp_ne_u32_e64 s[2:3], 1, v8
	v_add_u32_e32 v45, v6, v7
	v_readlane_b32 s10, v254, 44
	v_readlane_b32 s11, v254, 45
	v_readlane_b32 s12, v254, 46
	v_readlane_b32 s13, v254, 47
	v_readlane_b32 s14, v254, 48
	v_readlane_b32 s15, v254, 49
	v_readlane_b32 s16, v254, 50
	v_readlane_b32 s17, v254, 51
	v_readlane_b32 s18, v254, 52
	v_readlane_b32 s19, v254, 53
	v_readlane_b32 s22, v254, 56
	v_readlane_b32 s23, v254, 57
	s_branch .LBB0_950

; #define LAS __attribute__((address_space(3)))
; template <int NKS, bool ATILED = false, bool FFN = false, bool HALF = false, class EF> ...
;     const int lane = tid & 63, w = __builtin_amdgcn_readfirstlane(tid >> 6), c16 = lane & 15, kq = lane >> 4;
;     static_assert(NKS % 2 == 0, "the waves' K slices are whole 32-wide k-steps");
;     constexpr int kw = NKS * 16, K = kw * 8, NS = NKS / 2;
;     constexpr int RB = HALF ? 32 : 64, MI = RB / 16; const int ncb = N >> 6, npieces = (512 / RB) * ncb;
;     if (bid < first || bid >= first + ncu) return;
;     LAS float* lf = (LAS float*)lds;
; #pragma unroll 1
;     for (int pc = bid - first;; pc += ncu) {
;         if (qctr) { __syncthreads(); if (tid == 0) qslot[0] = (int)atomicAdd(qctr, 1u); __syncthreads(); pc = __builtin_amdgcn_readfirstlane(qslot[0]); }
;         if (pc >= npieces) break;
;         const int rb = pc / ncb, cb = pc - rb * ncb;
;         const bf16* a0 = ATILED ? A + (size_t)(MP + RB * rb + c16) * 64 : A + (size_t)(RB * rb + c16) * K + w * kw + 8 * kq;
;         const bf16* b0 = Wt + (size_t)((cb >> 2) * 256 + 32 * (cb & 3) + c16) * K + w * kw + 8 * kq;
; __global__ void __launch_bounds__(512, 2) mk_fwd(Args a) {
;     ...
;         mini_gemm<8>((const bf16*)(ws + WS_CO) + (size_t)MP * DMODEL, (const bf16*)(ws + WS_WO), DMODEL, 0, G, bid, lds, tid,
;                   mef::Res<true>{(const bf16*)(ws + WS_XB1) + (size_t)MP * DMODEL, (bf16*)(ws + WS_XB2), (float*)(ws + WS_SS2)});
.LBB0_952:
	v_readlane_b32 s0, v255, 53
	s_cmp_lg_u32 s0, 0
	s_cbranch_scc1 .Lp7_after
	s_add_u32 s33, s94, 0xf00000
	s_addc_u32 s38, s95, 0
	s_add_u32 s6, s94, 0x1d700000
	s_addc_u32 s7, s95, 0
	s_add_u32 s8, s94, 0x3400000
	s_addc_u32 s9, s95, 0
	s_cmp_lt_i32 s96, 0
	s_cselect_b64 s[2:3], -1, 0
	s_cmp_ge_i32 s96, s75
	s_cselect_b64 s[4:5], -1, 0
	s_or_b64 s[2:3], s[2:3], s[4:5]
	s_cmpk_gt_u32 s96, 0x7f
	s_cselect_b64 s[4:5], -1, 0
	v_and_b32_e32 v18, 15, v0
	s_or_b64 s[2:3], s[2:3], s[4:5]
	v_readfirstlane_b32 s0, v0
	s_andn2_b64 vcc, exec, s[2:3]
	v_lshlrev_b32_e32 v20, 2, v18
	s_cbranch_vccz .LBB0_957
	s_add_u32 s2, s94, 0x15200000
	s_addc_u32 s3, s95, 0
	s_lshr_b32 s4, s0, 6
	s_lshl_b32 s5, s4, 8
	v_bfe_u32 v19, v0, 4, 2
	s_add_u32 s0, s94, s5
	s_addc_u32 s1, s95, 0
	v_lshlrev_b32_e32 v4, 4, v19
	v_mov_b32_e32 v5, 0
	v_lshl_add_u64 v[2:3], s[0:1], 0, v[4:5]
	s_mov_b64 s[0:1], 0x19400000
	v_lshl_add_u64 v[2:3], v[2:3], 0, s[0:1]
	s_add_u32 s0, s33, s5
	s_addc_u32 s1, s38, 0
	v_lshlrev_b32_e32 v7, 3, v0
	v_lshl_add_u64 v[4:5], s[0:1], 0, v[4:5]
	s_lshl_b32 s0, s4, 14
	v_lshrrev_b32_e32 v1, 3, v0
	v_and_b32_e32 v22, 56, v7
	v_lshlrev_b32_e32 v6, 10, v19
	s_add_i32 s0, s0, 0
	v_lshlrev_b32_e32 v7, 8, v1
	v_lshlrev_b32_e32 v8, 2, v22
	v_add3_u32 v23, 0, v7, v8
	v_and_b32_e32 v7, 7, v0
	v_add3_u32 v24, s0, v20, v6
	v_lshlrev_b32_e32 v21, 3, v19
	v_cmp_eq_u32_e32 vcc, 0, v7
	s_mov_b32 s10, 0x10000
	v_add_u32_e32 v25, 0x10000, v23
	v_add_u32_e32 v26, 0x10010, v23
	v_add_u32_e32 v27, 0x14000, v23
	v_add_u32_e32 v28, 0x14010, v23
	s_mov_b32 s11, 0x18000
	v_add_u32_e32 v29, 0x18000, v23
	v_add_u32_e32 v30, 0x18010, v23
	v_add_u32_e32 v31, 0x1c000, v23
	v_add_u32_e32 v32, 0x1c010, v23
	s_lshl_b32 s12, s96, 5
	s_lshl_b32 s13, s75, 5
	s_lshl_b32 s14, s96, 6
	s_lshl_b32 s15, s75, 6
	s_mov_b32 s16, 0x8000
	s_mov_b32 s17, 0x40000
	s_mov_b32 s18, 0x48000
	s_mov_b64 s[4:5], 0x4000
	v_add_u32_e32 v33, 0x1000, v24
	v_add_u32_e32 v34, 0x2000, v24
	v_add_u32_e32 v35, 0x3000, v24
	s_mov_b32 s19, s96
	s_branch .LBB0_955

; #define GRID_BAR() do { if (MK_ONE_LAUNCH) { xcd_barrier(bar); if (MK_DBL == 99) xcd_barrier(bar); } } while (0)
; #define BOTH(k) (IN(k) && IN((k) + 1))
; __global__ void __launch_bounds__(512, 2) mk_fwd(Args a) {
;     ...
;         if (BOTH(7)) GRID_BAR();
.Lp7_after:
	s_cmp_lt_i32 s85, 9
	s_cbranch_scc1 .LBB0_1056
	s_branch .LBB0_1003
